# W_in epilogue: the four per-head gain-vector loads issued together with one drain instead of four load/drain round trips
# speedup vs baseline: 1.0079x; 1.0030x over previous
; #define PG8_LAS __attribute__((address_space(3)))
;     __device__ __forceinline__ void operator()(const f32x4 (&acc)[2][2][4][2], const Unit& u, int wr, int wc, int fr, int fq) const {
;     ...
;         const bool donorm = (seg != 2) && (seg != 5);
;         const float* g = (seg < 3) ? fox_g + (seg == 1 ? 64 : 0) : diff_g + (seg == 4 ? 64 : 0);
;         const float qs = (seg == 0 || seg == 3) ? 0.125f * kLog2e : 1.f;
;         f32x4 gv[2][2], bv[2][2];
;         P.issue(k + 1, wr == 0 && wc == 0, fr + 16 * fq);
;         PG8_LAS const float* slot = (PG8_LAS const float*)(P.pf + (k & 1) * 5120); ++k;
;         PG8_LAS const float* bp = slot + 1024 + 32 * wc + 8 * fq;
; #pragma unroll
;         for (int bj = 0; bj < 2; ++bj)
; #pragma unroll
;             for (int n = 0; n < 2; ++n) { gv[bj][n] = donorm ? (*(const f32x4*)(g + 32 * bj + 8 * fq + 4 * n)) * qs : (f32x4){1.f, 1.f, 1.f, 1.f}; bv[bj][n] = *(PG8_LAS const f32x4*)(bp + 128 * bj + 4 * n); }
.LBB0_408:
	s_or_b64 vcc, s[36:37], s[88:89]
	v_mov_b32_e32 v82, 0x3e38aa3b
	v_cndmask_b32_e32 v110, 1.0, v82, vcc
	v_mov_b32_e32 v202, 1.0
	v_lshl_add_u64 v[112:113], s[2:3], 0, v[0:1]
	v_mov_b32_e32 v111, v110
	s_andn2_b64 vcc, exec, s[30:31]
	v_mov_b32_e32 v203, v202
	v_mov_b32_e32 v204, v202
	v_mov_b32_e32 v205, v202
	s_mov_b32 s54, 0xc000
	s_cbranch_vccnz .LBB0_410
	global_load_dwordx4 v[82:85], v[112:113], off
	global_load_dwordx4 v[158:161], v[112:113], off offset:16
	global_load_dwordx4 v[162:165], v[112:113], off offset:128
	global_load_dwordx4 v[166:169], v[112:113], off offset:144
	v_mov_b32_e32 v86, v110
	v_mov_b32_e32 v87, v110
	s_waitcnt vmcnt(0)
	v_pk_mul_f32 v[204:205], v[86:87], v[84:85]
	v_pk_mul_f32 v[202:203], v[110:111], v[82:83]

; #define PG8_LAS __attribute__((address_space(3)))
;     __device__ __forceinline__ void operator()(const f32x4 (&acc)[2][2][4][2], const Unit& u, int wr, int wc, int fr, int fq) const {
;     ...
;         for (int bj = 0; bj < 2; ++bj)
; #pragma unroll
;             for (int n = 0; n < 2; ++n) { gv[bj][n] = donorm ? (*(const f32x4*)(g + 32 * bj + 8 * fq + 4 * n)) * qs : (f32x4){1.f, 1.f, 1.f, 1.f}; bv[bj][n] = *(PG8_LAS const f32x4*)(bp + 128 * bj + 4 * n); }
.LBB0_414:
	v_mov_b32_e32 v206, 1.0
	s_andn2_b64 vcc, exec, s[2:3]
	v_mov_b32_e32 v207, v206
	v_mov_b32_e32 v208, v206
	v_mov_b32_e32 v209, v206
	s_cbranch_vccnz .LBB0_416
	v_mov_b32_e32 v94, v110
	v_mov_b32_e32 v95, v110
	s_nop 0
	v_pk_mul_f32 v[208:209], v[94:95], v[160:161]
	v_pk_mul_f32 v[206:207], v[110:111], v[158:159]

; #define PG8_LAS __attribute__((address_space(3)))
;     __device__ __forceinline__ void operator()(const f32x4 (&acc)[2][2][4][2], const Unit& u, int wr, int wc, int fr, int fq) const {
;     ...
;         for (int bj = 0; bj < 2; ++bj)
; #pragma unroll
;             for (int n = 0; n < 2; ++n) { gv[bj][n] = donorm ? (*(const f32x4*)(g + 32 * bj + 8 * fq + 4 * n)) * qs : (f32x4){1.f, 1.f, 1.f, 1.f}; bv[bj][n] = *(PG8_LAS const f32x4*)(bp + 128 * bj + 4 * n); }
.LBB0_420:
	v_mov_b32_e32 v210, 1.0
	s_andn2_b64 vcc, exec, s[2:3]
	v_mov_b32_e32 v211, v210
	v_mov_b32_e32 v212, v210
	v_mov_b32_e32 v213, v210
	s_cbranch_vccnz .LBB0_422
	v_mov_b32_e32 v116, v110
	v_mov_b32_e32 v117, v110
	s_nop 0
	v_pk_mul_f32 v[212:213], v[116:117], v[164:165]
	v_pk_mul_f32 v[210:211], v[110:111], v[162:163]

; #define PG8_LAS __attribute__((address_space(3)))
;     __device__ __forceinline__ void operator()(const f32x4 (&acc)[2][2][4][2], const Unit& u, int wr, int wc, int fr, int fq) const {
;     ...
;         for (int bj = 0; bj < 2; ++bj)
; #pragma unroll
;             for (int n = 0; n < 2; ++n) { gv[bj][n] = donorm ? (*(const f32x4*)(g + 32 * bj + 8 * fq + 4 * n)) * qs : (f32x4){1.f, 1.f, 1.f, 1.f}; bv[bj][n] = *(PG8_LAS const f32x4*)(bp + 128 * bj + 4 * n); }
.LBB0_426:
	v_mov_b32_e32 v214, 1.0
	s_andn2_b64 vcc, exec, s[2:3]
	v_mov_b32_e32 v215, v214
	v_mov_b32_e32 v216, v214
	v_mov_b32_e32 v217, v214
	s_cbranch_vccnz .LBB0_428
	v_mov_b32_e32 v112, v110
	v_mov_b32_e32 v113, v110
	s_nop 0
	v_pk_mul_f32 v[216:217], v[112:113], v[168:169]
	v_pk_mul_f32 v[214:215], v[110:111], v[166:167]
